# prologue x->bf16 rows pass and final RMSNorm pass: loads hoisted ahead of stores (one round trip per row instead of eight), gains preloaded
# speedup vs baseline: 1.0110x; 1.0110x over previous
.LBB0_10:
	s_movk_i32 s0, 0x1400
	v_writelane_b32 v247, s0, 0
	s_movk_i32 s0, 0x1000
	s_nop 0
	v_writelane_b32 v247, s0, 8
	s_movk_i32 s0, 0x7fff
	s_nop 0
	v_writelane_b32 v247, s0, 9
	s_mov_b32 s0, 0
	s_nop 1
	v_writelane_b32 v247, s0, 1
	s_nop 1
	v_writelane_b32 v247, s0, 3
	s_nop 1
	v_writelane_b32 v247, s0, 6
	s_movk_i32 s0, 0xb00
	s_nop 0
	v_writelane_b32 v247, s0, 2
	s_movk_i32 s0, 0x2800
	s_nop 0
	v_writelane_b32 v247, s0, 5
	s_waitcnt lgkmcnt(0)
	s_lshl_b32 s0, s66, 3
	s_nop 0
	v_writelane_b32 v247, s0, 4
	s_lshr_b32 s100, s2, 6
	s_lshl_b32 s0, s74, 3
	s_add_i32 s100, s100, s0

.LBB0_133:
	v_lshl_add_u64 v[12:13], s[64:65], 0, v[6:7]
	v_add_co_u32_e64 v40, s[6:7], s2, v12
	global_load_dwordx4 v[8:11], v[4:5], off offset:-4096
	global_load_dwordx4 v[192:195], v[4:5], off offset:-3072
	global_load_dwordx4 v[196:199], v[4:5], off offset:-2048
	global_load_dwordx4 v[200:203], v[4:5], off offset:-1024
	global_load_dwordx4 v[204:207], v[4:5], off
	global_load_dwordx4 v[208:211], v[4:5], off offset:1024
	global_load_dwordx4 v[212:215], v[4:5], off offset:2048
	global_load_dwordx4 v[216:219], v[4:5], off offset:3072
	s_nop 0
	v_addc_co_u32_e64 v41, s[6:7], 0, v13, s[6:7]
	s_waitcnt vmcnt(7)
	v_cvt_pk_bf16_f32 v12, v8, v9
	v_cvt_pk_bf16_f32 v13, v10, v11
	global_store_dwordx2 v[40:41], v[12:13], off
	s_waitcnt vmcnt(7)
	v_mov_b32_e32 v12, v192
	v_mov_b32_e32 v13, v193
	v_mov_b32_e32 v14, v194
	v_mov_b32_e32 v15, v195
	v_cvt_pk_bf16_f32 v16, v12, v13
	v_cvt_pk_bf16_f32 v17, v14, v15
	global_store_dwordx2 v[40:41], v[16:17], off offset:512
	s_waitcnt vmcnt(7)
	v_mov_b32_e32 v16, v196
	v_mov_b32_e32 v17, v197
	v_mov_b32_e32 v18, v198
	v_mov_b32_e32 v19, v199
	v_cvt_pk_bf16_f32 v20, v16, v17
	v_cvt_pk_bf16_f32 v21, v18, v19
	global_store_dwordx2 v[40:41], v[20:21], off offset:1024
	s_waitcnt vmcnt(7)
	v_mov_b32_e32 v20, v200
	v_mov_b32_e32 v21, v201
	v_mov_b32_e32 v22, v202
	v_mov_b32_e32 v23, v203
	v_cvt_pk_bf16_f32 v24, v20, v21
	v_cvt_pk_bf16_f32 v25, v22, v23
	global_store_dwordx2 v[40:41], v[24:25], off offset:1536
	s_waitcnt vmcnt(7)
	v_mov_b32_e32 v24, v204
	v_mov_b32_e32 v25, v205
	v_mov_b32_e32 v26, v206
	v_mov_b32_e32 v27, v207
	v_cvt_pk_bf16_f32 v28, v24, v25
	v_cvt_pk_bf16_f32 v29, v26, v27
	global_store_dwordx2 v[40:41], v[28:29], off offset:2048
	s_waitcnt vmcnt(7)
	v_mov_b32_e32 v28, v208
	v_mov_b32_e32 v29, v209
	v_mov_b32_e32 v30, v210
	v_mov_b32_e32 v31, v211
	v_cvt_pk_bf16_f32 v32, v28, v29
	v_cvt_pk_bf16_f32 v33, v30, v31
	global_store_dwordx2 v[40:41], v[32:33], off offset:2560
	s_waitcnt vmcnt(7)
	v_mov_b32_e32 v32, v212
	v_mov_b32_e32 v33, v213
	v_mov_b32_e32 v34, v214
	v_mov_b32_e32 v35, v215
	v_cvt_pk_bf16_f32 v36, v32, v33
	v_cvt_pk_bf16_f32 v37, v34, v35
	global_store_dwordx2 v[40:41], v[36:37], off offset:3072
	v_mov_b32_e32 v42, 0
	v_mul_f32_e32 v9, v9, v9
	v_mul_f32_e32 v11, v11, v11
	v_fmac_f32_e32 v9, v8, v8
	v_fmac_f32_e32 v11, v10, v10
	v_add_f32_e32 v8, v9, v11
	v_mul_f32_e32 v9, v13, v13
	v_mul_f32_e32 v10, v15, v15
	v_fmac_f32_e32 v9, v12, v12
	v_fmac_f32_e32 v10, v14, v14
	v_add_f32_e32 v9, v9, v10
	v_add_f32_e32 v8, v8, v9
	v_mul_f32_e32 v9, v17, v17
	v_mul_f32_e32 v10, v19, v19
	v_fmac_f32_e32 v9, v16, v16
	v_fmac_f32_e32 v10, v18, v18
	v_add_f32_e32 v9, v9, v10
	v_add_f32_e32 v8, v8, v9
	v_mul_f32_e32 v9, v21, v21
	v_mul_f32_e32 v10, v23, v23
	v_fmac_f32_e32 v9, v20, v20
	v_fmac_f32_e32 v10, v22, v22
	v_add_f32_e32 v9, v9, v10
	v_add_f32_e32 v8, v8, v9
	v_mul_f32_e32 v9, v25, v25
	v_mul_f32_e32 v10, v27, v27
	v_fmac_f32_e32 v9, v24, v24
	v_fmac_f32_e32 v10, v26, v26
	v_add_f32_e32 v9, v9, v10
	v_add_f32_e32 v8, v8, v9
	v_mul_f32_e32 v9, v29, v29
	v_mul_f32_e32 v10, v31, v31
	v_fmac_f32_e32 v9, v28, v28
	v_fmac_f32_e32 v10, v30, v30
	v_add_f32_e32 v9, v9, v10
	v_add_f32_e32 v8, v8, v9
	v_mul_f32_e32 v9, v33, v33
	v_mul_f32_e32 v10, v35, v35
	v_fmac_f32_e32 v9, v32, v32
	v_fmac_f32_e32 v10, v34, v34
	v_add_f32_e32 v9, v9, v10
	s_waitcnt vmcnt(7)
	v_mov_b32_e32 v36, v216
	v_mov_b32_e32 v37, v217
	v_mov_b32_e32 v38, v218
	v_mov_b32_e32 v39, v219
	v_mul_f32_e32 v11, v37, v37
	v_mul_f32_e32 v12, v39, v39
	v_add_f32_e32 v10, v8, v9
	v_cvt_pk_bf16_f32 v8, v36, v37
	v_fmac_f32_e32 v11, v36, v36
	v_fmac_f32_e32 v12, v38, v38
	v_cvt_pk_bf16_f32 v9, v38, v39
	global_store_dwordx2 v[40:41], v[8:9], off offset:3584
	v_add_f32_e32 v8, v11, v12
	v_add_f32_e32 v8, v10, v8
	v_mov_b32_e32 v9, 0
	s_nop 0
	v_add_f32_dpp v8, v8, v8 row_shr:1 row_mask:0xf bank_mask:0xf bound_ctrl:1
	s_nop 1
	v_add_f32_dpp v8, v8, v8 row_shr:2 row_mask:0xf bank_mask:0xf bound_ctrl:1
	s_nop 1
	v_add_f32_dpp v8, v8, v8 row_shr:4 row_mask:0xf bank_mask:0xf bound_ctrl:1
	s_nop 1
	v_add_f32_dpp v8, v8, v8 row_shr:8 row_mask:0xf bank_mask:0xf bound_ctrl:1
	s_nop 1
	v_mov_b32_dpp v42, v8 row_bcast:15 row_mask:0xa bank_mask:0xf
	v_add_f32_e32 v8, v8, v42
	s_nop 1
	v_mov_b32_dpp v9, v8 row_bcast:31 row_mask:0xc bank_mask:0xf
	v_add_f32_e32 v8, v8, v9
	s_nop 0
	v_readlane_b32 s14, v8, 63
	s_and_saveexec_b64 s[6:7], s[4:5]
	s_cbranch_execz .LBB0_132
	v_mov_b32_e32 v8, s14
	v_cndmask_b32_e32 v10, 0, v8, vcc
	v_lshl_add_u64 v[8:9], s[64:65], 0, v[2:3]
	global_store_dword v[8:9], v10, off
	s_branch .LBB0_132

.Lwin_all:
	v_writelane_b32 v242, s0, 0
	s_nop 1
	v_writelane_b32 v242, s1, 1
	s_nop 1
	v_writelane_b32 v242, s2, 2
	s_nop 1
	v_writelane_b32 v242, s3, 3
	s_nop 1
	v_writelane_b32 v242, s4, 4
	s_nop 1
	v_writelane_b32 v242, s5, 5
	s_nop 1
	v_writelane_b32 v242, s6, 6
	s_nop 1
	v_writelane_b32 v242, s7, 7
	s_nop 1
	v_writelane_b32 v242, s8, 8
	s_nop 1
	v_writelane_b32 v242, s9, 9
	s_nop 1
	v_writelane_b32 v242, s10, 10
	s_nop 1
	v_writelane_b32 v242, s11, 11
	s_nop 1
	v_writelane_b32 v242, s12, 12
	s_nop 1
	v_writelane_b32 v242, s13, 13
	s_nop 1
	v_writelane_b32 v242, s14, 14
	s_nop 1
	v_writelane_b32 v242, s15, 15
	s_nop 1
	v_writelane_b32 v242, s16, 16
	s_nop 1
	v_writelane_b32 v242, s17, 17
	s_nop 1
	v_writelane_b32 v242, s18, 18
	s_nop 1
	v_writelane_b32 v242, s19, 19
	s_nop 1
	v_writelane_b32 v242, s20, 20
	s_nop 1
	v_writelane_b32 v242, s21, 21
	s_nop 1
	v_writelane_b32 v242, s22, 22
	s_nop 1
	v_writelane_b32 v242, s23, 23
	s_nop 1
	v_writelane_b32 v242, s24, 24
	s_nop 1
	v_writelane_b32 v242, s25, 25
	s_nop 1
	v_writelane_b32 v242, s26, 26
	s_nop 1
	v_writelane_b32 v242, s27, 27
	s_nop 1
	v_writelane_b32 v242, s28, 28
	s_nop 1
	v_writelane_b32 v242, s29, 29
	s_nop 1
	v_writelane_b32 v242, s30, 30
	s_nop 1
	v_writelane_b32 v242, s31, 31
	s_nop 1
	v_writelane_b32 v242, s32, 32
	s_nop 1
	v_writelane_b32 v242, s33, 33
	s_nop 1
	v_writelane_b32 v242, s34, 34
	s_nop 1
	v_writelane_b32 v242, s35, 35
	s_nop 1
	v_writelane_b32 v242, s36, 36
	s_nop 1
	v_writelane_b32 v242, s37, 37
	s_nop 1
	v_writelane_b32 v242, s38, 38
	s_nop 1
	v_writelane_b32 v242, s39, 39
	s_nop 1
	v_writelane_b32 v242, s40, 40
	s_nop 1
	v_writelane_b32 v242, s41, 41
	s_nop 1
	v_writelane_b32 v242, s42, 42
	s_nop 1
	v_writelane_b32 v242, s43, 43
	s_nop 1
	v_writelane_b32 v242, s44, 44
	s_nop 1
	v_writelane_b32 v242, s45, 45
	s_nop 1
	v_writelane_b32 v242, s46, 46
	s_nop 1
	v_writelane_b32 v242, s47, 47
	s_nop 1
	v_writelane_b32 v242, s48, 48
	s_nop 1
	v_writelane_b32 v242, s49, 49
	s_nop 1
	v_writelane_b32 v242, s50, 50
	s_nop 1
	v_writelane_b32 v242, s51, 51
	s_nop 1
	v_writelane_b32 v242, s52, 52
	s_nop 1
	v_writelane_b32 v242, s53, 53
	s_nop 1
	v_writelane_b32 v242, s54, 54
	s_nop 1
	v_writelane_b32 v242, s55, 55
	s_nop 1
	v_writelane_b32 v242, s56, 56
	s_nop 1
	v_writelane_b32 v242, s57, 57
	s_nop 1
	v_writelane_b32 v242, s58, 58
	s_nop 1
	v_writelane_b32 v242, s59, 59
	s_nop 1
	v_writelane_b32 v242, s60, 60
	s_nop 1
	v_writelane_b32 v242, s61, 61
	s_nop 1
	v_writelane_b32 v242, s62, 62
	s_nop 1
	v_writelane_b32 v242, s63, 63
	s_nop 1
	v_writelane_b32 v243, s64, 0
	s_nop 1
	v_writelane_b32 v243, s65, 1
	s_nop 1
	v_writelane_b32 v243, s66, 2
	s_nop 1
	v_writelane_b32 v243, s67, 3
	s_nop 1
	v_writelane_b32 v243, s68, 4
	s_nop 1
	v_writelane_b32 v243, s69, 5
	s_nop 1
	v_writelane_b32 v243, s70, 6
	s_nop 1
	v_writelane_b32 v243, s71, 7
	s_nop 1
	v_writelane_b32 v243, s72, 8
	s_nop 1
	v_writelane_b32 v243, s73, 9
	s_nop 1
	v_writelane_b32 v243, s74, 10
	s_nop 1
	v_writelane_b32 v243, s75, 11
	s_nop 1
	v_writelane_b32 v243, s76, 12
	s_nop 1
	v_writelane_b32 v243, s77, 13
	s_nop 1
	v_writelane_b32 v243, s78, 14
	s_nop 1
	v_writelane_b32 v243, s79, 15
	s_nop 1
	v_writelane_b32 v243, s80, 16
	s_nop 1
	v_writelane_b32 v243, s81, 17
	s_nop 1
	v_writelane_b32 v243, s82, 18
	s_nop 1
	v_writelane_b32 v243, s83, 19
	s_nop 1
	v_writelane_b32 v243, s84, 20
	s_nop 1
	v_writelane_b32 v243, s85, 21
	s_nop 1
	v_writelane_b32 v243, s86, 22
	s_nop 1
	v_writelane_b32 v243, s87, 23
	s_nop 1
	v_writelane_b32 v243, s88, 24
	s_nop 1
	v_writelane_b32 v243, s89, 25
	s_nop 1
	v_writelane_b32 v243, s90, 26
	s_nop 1
	v_writelane_b32 v243, s91, 27
	s_nop 1
	v_writelane_b32 v243, s92, 28
	s_nop 1
	v_writelane_b32 v243, s93, 29
	s_nop 1
	v_writelane_b32 v243, s94, 30
	s_nop 1
	v_writelane_b32 v243, s95, 31
	s_nop 1
	v_writelane_b32 v243, s96, 32
	s_nop 1
	v_writelane_b32 v243, s97, 33
	s_nop 1
	v_writelane_b32 v243, s98, 34
	s_nop 1
	v_writelane_b32 v243, s99, 35
	s_nop 1
	v_writelane_b32 v243, vcc_lo, 36
	s_nop 1
	v_writelane_b32 v243, vcc_hi, 37
	s_mov_b64 s[0:1], exec
	s_nop 1
	v_writelane_b32 v243, s0, 38
	s_nop 1
	v_writelane_b32 v243, s1, 39
	s_mov_b64 exec, -1
	v_mov_b32_e32 v244, v241
	v_mov_b32_e32 v245, v4
	v_mov_b32_e32 v246, v33
	s_cmp_gt_u32 s70, 2
	s_cselect_b32 s4, 1, 0
	s_nop 0
	v_writelane_b32 v247, s4, 3
	s_movk_i32 s4, 0x1280
	s_nop 0
	v_writelane_b32 v247, s4, 0
	s_nop 1
	v_writelane_b32 v247, s4, 5
	s_movk_i32 s4, 0x7fff
	s_nop 0
	v_writelane_b32 v247, s4, 9
	s_nop 1
	v_writelane_b32 v247, s4, 8
	s_movk_i32 s4, 0xb00
	s_nop 0
	v_writelane_b32 v247, s4, 1
	s_movk_i32 s4, 0x1400
	s_nop 0
	v_writelane_b32 v247, s4, 2
	s_lshl_b32 s4, s66, 3
	s_cmpk_eq_i32 s66, 0x100
	s_cselect_b32 s4, 0x400, s4
	s_cselect_b32 s3, 0x400, 0
	s_nop 0
	v_writelane_b32 v247, s4, 4
	s_mov_b32 s4, 1
	s_nop 0
	v_writelane_b32 v247, s4, 6
	s_load_dwordx8 s[8:15], s[30:31], 0x0
	s_load_dwordx4 s[24:27], s[30:31], 0x20
	s_load_dwordx2 s[6:7], s[30:31], 0x30
	s_load_dwordx4 s[64:67], s[30:31], 0xb0
	v_readfirstlane_b32 s2, v156
	s_lshl_b32 s4, s74, 3
	s_lshr_b32 s100, s2, 6
	s_add_i32 s100, s100, s4
	s_sub_i32 s100, s100, s3
	s_waitcnt lgkmcnt(0)
	s_branch .Lconv_pre

.LBB0_633:
	v_readlane_b32 s0, v240, 11
	v_readlane_b32 s1, v240, 12
	s_andn2_b64 vcc, exec, s[0:1]
	s_cbranch_vccnz .LBB0_638
	s_load_dwordx4 s[4:7], s[30:31], 0xa0
	s_load_dwordx2 s[2:3], s[30:31], 0xb0
	v_lshlrev_b32_e32 v14, 5, v157
	v_mov_b32_e32 v15, 0
	v_or_b32_e32 v2, 0x1000, v14
	v_mov_b32_e32 v3, v15
	v_or_b32_e32 v4, 0x1010, v14
	v_mov_b32_e32 v5, v15
	v_or_b32_e32 v6, 0x1800, v14
	v_mov_b32_e32 v7, v15
	v_or_b32_e32 v8, 0x1810, v14
	v_mov_b32_e32 v9, v15
	s_waitcnt lgkmcnt(0)
	v_lshl_add_u64 v[0:1], s[4:5], 0, v[14:15]
	v_lshl_add_u64 v[2:3], s[4:5], 0, v[2:3]
	v_lshl_add_u64 v[4:5], s[4:5], 0, v[4:5]
	v_lshl_add_u64 v[6:7], s[4:5], 0, v[6:7]
	v_lshl_add_u64 v[8:9], s[4:5], 0, v[8:9]
	v_readlane_b32 s4, v241, 2
	v_readlane_b32 s5, v241, 3
	s_mov_b32 s10, s4
	s_ashr_i32 s11, s4, 31
	s_lshl_b64 s[4:5], s[10:11], 12
	v_lshl_or_b32 v10, v157, 4, s4
	v_mov_b32_e32 v11, s5
	v_readlane_b32 s4, v241, 0
	v_readlane_b32 s5, v241, 1
	s_mov_b32 s12, s4
	s_ashr_i32 s13, s4, 31
	s_lshl_b64 s[4:5], s[12:13], 12
	s_lshl_b64 s[8:9], s[10:11], 13
	s_add_u32 s6, s6, s8
	s_addc_u32 s7, s7, s9
	s_lshl_b64 s[8:9], s[10:11], 7
	v_mov_b32_e32 v159, v15
	v_lshl_add_u64 v[12:13], s[6:7], 0, v[14:15]
	s_mov_b64 s[6:7], 0x1810
	v_lshl_add_u64 v[14:15], s[8:9], 0, v[158:159]
	s_mov_b64 s[8:9], 0x23400000
	v_cmp_gt_u32_e64 s[0:1], 32, v157
	v_lshl_add_u64 v[12:13], v[12:13], 0, s[6:7]
	s_lshl_b64 s[6:7], s[12:13], 13
	s_mov_b32 s16, s10
	v_lshl_add_u64 v[14:15], v[14:15], 0, s[8:9]
	s_mov_b32 s18, s12
	s_lshl_b64 s[8:9], s[12:13], 7
	v_mov_b32_e32 v16, 0x3727c5ac
	v_mov_b32_e32 v17, 0x3a000000
	s_mov_b32 s12, 0x13800000
	s_movk_i32 s13, 0xf000
	global_load_dwordx4 v[192:195], v[0:1], off
	global_load_dwordx4 v[196:199], v[0:1], off offset:16
	global_load_dwordx4 v[200:203], v[0:1], off offset:2048
	global_load_dwordx4 v[204:207], v[0:1], off offset:2064
	global_load_dwordx4 v[208:211], v[2:3], off
	global_load_dwordx4 v[212:215], v[4:5], off
	global_load_dwordx4 v[216:219], v[6:7], off
	global_load_dwordx4 v[220:223], v[8:9], off
	s_waitcnt vmcnt(0)
	s_branch .LBB0_636
.LBB0_635:
	s_or_b64 exec, exec, s[10:11]
	v_lshl_add_u64 v[20:21], s[2:3], 0, v[10:11]
	v_add_co_u32_e32 v28, vcc, s12, v20
	s_nop 1
	v_addc_co_u32_e32 v29, vcc, 0, v21, vcc
	global_load_dwordx4 v[224:227], v[28:29], off
	global_load_dwordx4 v[228:231], v[28:29], off offset:1024
	global_load_dwordx4 v[232:235], v[28:29], off offset:2048
	global_load_dwordx4 v[236:239], v[28:29], off offset:3072
	s_waitcnt vmcnt(4)
	v_add_f32_dpp v18, v18, v18 row_shr:1 row_mask:0xf bank_mask:0xf bound_ctrl:1
	s_nop 1
	v_add_f32_dpp v18, v18, v18 row_shr:2 row_mask:0xf bank_mask:0xf bound_ctrl:1
	v_mov_b32_e32 v19, 0
	v_mov_b32_e32 v32, 0
	v_add_f32_dpp v18, v18, v18 row_shr:4 row_mask:0xf bank_mask:0xf bound_ctrl:1
	v_add_co_u32_e32 v30, vcc, s13, v12
	s_nop 0
	v_add_f32_dpp v18, v18, v18 row_shr:8 row_mask:0xf bank_mask:0xf bound_ctrl:1
	v_addc_co_u32_e32 v31, vcc, -1, v13, vcc
	s_nop 0
	v_mov_b32_dpp v19, v18 row_bcast:15 row_mask:0xa bank_mask:0xf
	v_add_f32_e32 v18, v18, v19
	v_lshl_add_u64 v[10:11], v[10:11], 0, s[4:5]
	v_lshl_add_u64 v[14:15], v[14:15], 0, s[8:9]
	v_mov_b32_dpp v32, v18 row_bcast:31 row_mask:0xc bank_mask:0xf
	v_add_f32_e32 v18, v18, v32
	s_waitcnt vmcnt(3)
	v_mov_b32_e32 v20, v224
	v_mov_b32_e32 v21, v225
	v_mov_b32_e32 v22, v226
	v_mov_b32_e32 v23, v227
	v_and_b32_e32 v19, 0xffff0000, v20
	v_readlane_b32 s10, v18, 63
	s_nop 1
	v_fma_f32 v18, s10, v17, v16
	v_rsq_f32_e32 v32, v18
	v_lshlrev_b32_e32 v18, 16, v20
	v_lshlrev_b32_e32 v20, 16, v21
	v_and_b32_e32 v21, 0xffff0000, v21
	v_pk_mul_f32 v[18:19], v[32:33], v[18:19] op_sel_hi:[0,1]
	v_pk_mul_f32 v[20:21], v[32:33], v[20:21] op_sel_hi:[0,1]
	v_mov_b32_e32 v24, v192
	v_mov_b32_e32 v25, v193
	v_mov_b32_e32 v26, v194
	v_mov_b32_e32 v27, v195
	v_pk_mul_f32 v[20:21], v[26:27], v[20:21]
	v_pk_mul_f32 v[18:19], v[24:25], v[18:19]
	global_store_dwordx4 v[30:31], v[18:21], off offset:-2064
	v_lshlrev_b32_e32 v24, 16, v22
	v_and_b32_e32 v25, 0xffff0000, v22
	v_lshlrev_b32_e32 v22, 16, v23
	v_and_b32_e32 v23, 0xffff0000, v23
	v_pk_mul_f32 v[22:23], v[32:33], v[22:23] op_sel_hi:[0,1]
	v_pk_mul_f32 v[24:25], v[32:33], v[24:25] op_sel_hi:[0,1]
	s_add_i32 s10, s16, s18
	s_mov_b32 s16, s10
	s_cmpk_gt_i32 s10, 0x3fff
	v_mov_b32_e32 v18, v196
	v_mov_b32_e32 v19, v197
	v_mov_b32_e32 v20, v198
	v_mov_b32_e32 v21, v199
	v_pk_mul_f32 v[18:19], v[18:19], v[24:25]
	v_pk_mul_f32 v[20:21], v[20:21], v[22:23]
	global_store_dwordx4 v[30:31], v[18:21], off offset:-2048
	s_nop 1
	s_waitcnt vmcnt(4)
	v_mov_b32_e32 v18, v228
	v_mov_b32_e32 v19, v229
	v_mov_b32_e32 v20, v230
	v_mov_b32_e32 v21, v231
	v_mov_b32_e32 v22, v200
	v_mov_b32_e32 v23, v201
	v_mov_b32_e32 v24, v202
	v_mov_b32_e32 v25, v203
	v_lshlrev_b32_e32 v26, 16, v18
	v_and_b32_e32 v27, 0xffff0000, v18
	v_lshlrev_b32_e32 v18, 16, v19
	v_and_b32_e32 v19, 0xffff0000, v19
	v_pk_mul_f32 v[26:27], v[32:33], v[26:27] op_sel_hi:[0,1]
	v_pk_mul_f32 v[18:19], v[32:33], v[18:19] op_sel_hi:[0,1]
	v_pk_mul_f32 v[24:25], v[24:25], v[18:19]
	v_pk_mul_f32 v[22:23], v[22:23], v[26:27]
	global_store_dwordx4 v[30:31], v[22:25], off offset:-16
	s_nop 1
	v_mov_b32_e32 v22, v204
	v_mov_b32_e32 v23, v205
	v_mov_b32_e32 v24, v206
	v_mov_b32_e32 v25, v207
	v_lshlrev_b32_e32 v18, 16, v20
	v_and_b32_e32 v19, 0xffff0000, v20
	v_lshlrev_b32_e32 v20, 16, v21
	v_and_b32_e32 v21, 0xffff0000, v21
	v_pk_mul_f32 v[20:21], v[32:33], v[20:21] op_sel_hi:[0,1]
	v_pk_mul_f32 v[18:19], v[32:33], v[18:19] op_sel_hi:[0,1]
	v_pk_mul_f32 v[18:19], v[22:23], v[18:19]
	v_pk_mul_f32 v[20:21], v[24:25], v[20:21]
	global_store_dwordx4 v[12:13], v[18:21], off offset:-4096
	s_nop 1
	s_waitcnt vmcnt(5)
	v_mov_b32_e32 v18, v232
	v_mov_b32_e32 v19, v233
	v_mov_b32_e32 v20, v234
	v_mov_b32_e32 v21, v235
	v_mov_b32_e32 v22, v208
	v_mov_b32_e32 v23, v209
	v_mov_b32_e32 v24, v210
	v_mov_b32_e32 v25, v211
	v_lshlrev_b32_e32 v26, 16, v18
	v_and_b32_e32 v27, 0xffff0000, v18
	v_lshlrev_b32_e32 v18, 16, v19
	v_and_b32_e32 v19, 0xffff0000, v19
	v_pk_mul_f32 v[26:27], v[32:33], v[26:27] op_sel_hi:[0,1]
	v_pk_mul_f32 v[18:19], v[32:33], v[18:19] op_sel_hi:[0,1]
	v_pk_mul_f32 v[24:25], v[24:25], v[18:19]
	v_pk_mul_f32 v[22:23], v[22:23], v[26:27]
	global_store_dwordx4 v[12:13], v[22:25], off offset:-2064
	s_nop 1
	v_mov_b32_e32 v22, v212
	v_mov_b32_e32 v23, v213
	v_mov_b32_e32 v24, v214
	v_mov_b32_e32 v25, v215
	v_lshlrev_b32_e32 v18, 16, v20
	v_and_b32_e32 v19, 0xffff0000, v20
	v_lshlrev_b32_e32 v20, 16, v21
	v_and_b32_e32 v21, 0xffff0000, v21
	v_pk_mul_f32 v[20:21], v[32:33], v[20:21] op_sel_hi:[0,1]
	v_pk_mul_f32 v[18:19], v[32:33], v[18:19] op_sel_hi:[0,1]
	v_pk_mul_f32 v[18:19], v[22:23], v[18:19]
	v_pk_mul_f32 v[20:21], v[24:25], v[20:21]
	global_store_dwordx4 v[12:13], v[18:21], off offset:-2048
	s_nop 1
	s_waitcnt vmcnt(6)
	v_mov_b32_e32 v18, v236
	v_mov_b32_e32 v19, v237
	v_mov_b32_e32 v20, v238
	v_mov_b32_e32 v21, v239
	v_mov_b32_e32 v22, v216
	v_mov_b32_e32 v23, v217
	v_mov_b32_e32 v24, v218
	v_mov_b32_e32 v25, v219
	v_lshlrev_b32_e32 v26, 16, v18
	v_and_b32_e32 v27, 0xffff0000, v18
	v_lshlrev_b32_e32 v18, 16, v19
	v_and_b32_e32 v19, 0xffff0000, v19
	v_pk_mul_f32 v[26:27], v[32:33], v[26:27] op_sel_hi:[0,1]
	v_pk_mul_f32 v[18:19], v[32:33], v[18:19] op_sel_hi:[0,1]
	v_pk_mul_f32 v[24:25], v[24:25], v[18:19]
	v_pk_mul_f32 v[22:23], v[22:23], v[26:27]
	global_store_dwordx4 v[12:13], v[22:25], off offset:-16
	s_nop 1
	v_mov_b32_e32 v22, v220
	v_mov_b32_e32 v23, v221
	v_mov_b32_e32 v24, v222
	v_mov_b32_e32 v25, v223
	v_lshlrev_b32_e32 v18, 16, v20
	v_and_b32_e32 v19, 0xffff0000, v20
	v_lshlrev_b32_e32 v20, 16, v21
	v_and_b32_e32 v21, 0xffff0000, v21
	v_pk_mul_f32 v[20:21], v[32:33], v[20:21] op_sel_hi:[0,1]
	v_pk_mul_f32 v[18:19], v[32:33], v[18:19] op_sel_hi:[0,1]
	v_pk_mul_f32 v[18:19], v[22:23], v[18:19]
	v_pk_mul_f32 v[20:21], v[24:25], v[20:21]
	global_store_dwordx4 v[12:13], v[18:21], off
	v_lshl_add_u64 v[12:13], v[12:13], 0, s[6:7]
	s_cbranch_scc1 .LBB0_638
